# v58 + MLA: guarded fast path falls through (slow max/rescale path out of line); unit boundary waits for the next unit's DMA and Q loads before the output stores instead of for the stores
# speedup vs baseline: 1.0102x; 1.0102x over previous
.Lmla_noprio:
	s_waitcnt vmcnt(0)
	s_branch .LBB0_1473
.LBB0_1472:
	s_or_b64 exec, exec, s[22:23]
	v_add_u32_e32 v58, s42, v187
	ds_read_b128 v[50:53], v58 offset:41088
	ds_read_b128 v[54:57], v58 offset:41120
	s_add_i32 s22, s48, s12
	s_ashr_i32 s23, s22, 31
	s_add_u32 s14, s14, s22
	s_waitcnt lgkmcnt(1)
	v_rcp_f32_e32 v59, v50
	v_rcp_f32_e32 v60, v51
	v_rcp_f32_e32 v61, v52
	v_rcp_f32_e32 v62, v53
	v_mul_f32_e32 v18, v18, v59
	v_cvt_pk_bf16_f32 v18, v18, s0
	ds_write_b16 v188, v18 offset:43008
	v_mul_f32_e32 v18, v34, v59
	v_cvt_pk_bf16_f32 v18, v18, s0
	ds_write_b16 v188, v18 offset:43072
	v_mul_f32_e32 v18, v19, v60
	v_cvt_pk_bf16_f32 v18, v18, s0
	ds_write_b16 v188, v18 offset:43136
	v_mul_f32_e32 v18, v35, v60
	v_cvt_pk_bf16_f32 v18, v18, s0
	ds_write_b16 v188, v18 offset:43200
	v_mul_f32_e32 v18, v20, v61
	v_cvt_pk_bf16_f32 v18, v18, s0
	ds_write_b16 v188, v18 offset:43264
	v_mul_f32_e32 v18, v36, v61
	v_cvt_pk_bf16_f32 v18, v18, s0
	s_waitcnt lgkmcnt(5)
	v_rcp_f32_e32 v63, v54
	ds_write_b16 v188, v18 offset:43328
	v_mul_f32_e32 v18, v21, v62
	v_cvt_pk_bf16_f32 v18, v18, s0
	ds_write_b16 v188, v18 offset:43392
	v_mul_f32_e32 v18, v37, v62
	v_cvt_pk_bf16_f32 v18, v18, s0
	v_rcp_f32_e32 v64, v55
	ds_write_b16 v188, v18 offset:43456
	v_mul_f32_e32 v18, v22, v63
	v_cvt_pk_bf16_f32 v18, v18, s0
	ds_write_b16 v188, v18 offset:44032
	v_mul_f32_e32 v18, v38, v63
	v_cvt_pk_bf16_f32 v18, v18, s0
	v_rcp_f32_e32 v65, v56
	ds_write_b16 v188, v18 offset:44096
	v_mul_f32_e32 v18, v23, v64
	v_cvt_pk_bf16_f32 v18, v18, s0
	ds_write_b16 v188, v18 offset:44160
	v_mul_f32_e32 v18, v39, v64
	ds_read_b128 v[50:53], v58 offset:41152
	v_cvt_pk_bf16_f32 v18, v18, s0
	v_rcp_f32_e32 v66, v57
	ds_write_b16 v188, v18 offset:44224
	v_mul_f32_e32 v18, v24, v65
	v_cvt_pk_bf16_f32 v18, v18, s0
	ds_write_b16 v188, v18 offset:44288
	v_mul_f32_e32 v18, v40, v65
	v_cvt_pk_bf16_f32 v18, v18, s0
	ds_read_b128 v[54:57], v58 offset:41184
	s_waitcnt lgkmcnt(3)
	v_rcp_f32_e32 v50, v50
	ds_write_b16 v188, v18 offset:44352
	v_mul_f32_e32 v18, v25, v66
	v_cvt_pk_bf16_f32 v18, v18, s0
	ds_write_b16 v188, v18 offset:44416
	v_mul_f32_e32 v18, v41, v66
	v_cvt_pk_bf16_f32 v18, v18, s0
	v_rcp_f32_e32 v51, v51
	ds_write_b16 v188, v18 offset:44480
	v_mul_f32_e32 v18, v26, v50
	v_cvt_pk_bf16_f32 v18, v18, s0
	ds_write_b16 v188, v18 offset:45056
	v_mul_f32_e32 v18, v42, v50
	v_cvt_pk_bf16_f32 v18, v18, s0
	v_rcp_f32_e32 v52, v52
	ds_write_b16 v188, v18 offset:45120
	v_mul_f32_e32 v18, v27, v51
	v_cvt_pk_bf16_f32 v18, v18, s0
	ds_write_b16 v188, v18 offset:45184
	v_mul_f32_e32 v18, v43, v51
	v_cvt_pk_bf16_f32 v18, v18, s0
	v_rcp_f32_e32 v53, v53
	ds_write_b16 v188, v18 offset:45248
	v_mul_f32_e32 v18, v28, v52
	v_cvt_pk_bf16_f32 v18, v18, s0
	ds_write_b16 v188, v18 offset:45312
	v_mul_f32_e32 v18, v44, v52
	v_cvt_pk_bf16_f32 v18, v18, s0
	s_waitcnt lgkmcnt(8)
	v_rcp_f32_e32 v54, v54
	ds_write_b16 v188, v18 offset:45376
	v_mul_f32_e32 v18, v29, v53
	v_cvt_pk_bf16_f32 v18, v18, s0
	ds_write_b16 v188, v18 offset:45440
	v_mul_f32_e32 v18, v45, v53
	v_cvt_pk_bf16_f32 v18, v18, s0
	v_rcp_f32_e32 v55, v55
	ds_write_b16 v188, v18 offset:45504
	v_mul_f32_e32 v18, v30, v54
	v_cvt_pk_bf16_f32 v18, v18, s0
	ds_write_b16 v188, v18 offset:46080
	v_mul_f32_e32 v18, v46, v54
	v_cvt_pk_bf16_f32 v18, v18, s0
	v_rcp_f32_e32 v56, v56
	ds_write_b16 v188, v18 offset:46144
	v_mul_f32_e32 v18, v31, v55
	v_cvt_pk_bf16_f32 v18, v18, s0
	ds_write_b16 v188, v18 offset:46208
	v_mul_f32_e32 v18, v47, v55
	v_cvt_pk_bf16_f32 v18, v18, s0
	v_rcp_f32_e32 v57, v57
	ds_write_b16 v188, v18 offset:46272
	v_mul_f32_e32 v18, v32, v56
	v_cvt_pk_bf16_f32 v18, v18, s0
	ds_write_b16 v188, v18 offset:46336
	v_mul_f32_e32 v18, v48, v56
	v_cvt_pk_bf16_f32 v18, v18, s0
	ds_write_b16 v188, v18 offset:46400
	v_mul_f32_e32 v18, v33, v57
	v_cvt_pk_bf16_f32 v18, v18, s0
	s_addc_u32 s15, s15, s23
	ds_write_b16 v188, v18 offset:46464
	v_mul_f32_e32 v18, v49, v57
	s_lshl_b64 s[14:15], s[14:15], 11
	v_cvt_pk_bf16_f32 v18, v18, s0
	s_add_u32 s14, s3, s14
	ds_write_b16 v188, v18 offset:46528
	s_addc_u32 s15, s90, s15
	ds_read_b128 v[18:21], v191 offset:43008
	ds_read_b128 v[22:25], v192 offset:43008
	s_add_u32 s14, s14, s18
	s_addc_u32 s15, s15, s19
	v_lshl_add_u64 v[26:27], s[14:15], 0, v[166:167]
	v_mov_b32_e32 v173, v167
	v_lshl_add_u64 v[28:29], v[26:27], 0, v[172:173]
	v_mov_b32_e32 v175, v167
	s_waitcnt lgkmcnt(1)
	s_waitcnt vmcnt(0)
	global_store_dwordx4 v[28:29], v[18:21], off
	v_lshl_add_u64 v[28:29], v[26:27], 0, v[174:175]
	ds_read_b128 v[18:21], v193 offset:43008
	s_waitcnt lgkmcnt(1)
	global_store_dwordx4 v[28:29], v[22:25], off
	ds_read_b128 v[22:25], v194 offset:43008
	v_mov_b32_e32 v177, v167
	v_lshl_add_u64 v[28:29], v[26:27], 0, v[176:177]
	v_mov_b32_e32 v179, v167
	s_waitcnt lgkmcnt(1)
	global_store_dwordx4 v[28:29], v[18:21], off
	s_cmp_lg_u32 s26, s28
	s_mov_b32 s48, s50
	v_lshl_add_u64 v[18:19], v[26:27], 0, v[178:179]
	s_mov_b64 s[14:15], s[8:9]
	s_mov_b32 s50, s26
	s_waitcnt lgkmcnt(0)
	global_store_dwordx4 v[18:19], v[22:25], off
	s_cbranch_scc0 .LBB0_1496
.LBB0_1473:
	v_mov_b64_e32 v[32:33], v[16:17]
	v_mov_b64_e32 v[30:31], v[14:15]
	v_mov_b64_e32 v[28:29], v[12:13]
	v_mov_b64_e32 v[26:27], v[10:11]
	v_mov_b64_e32 v[24:25], v[8:9]
	v_mov_b64_e32 v[22:23], v[6:7]
	v_mov_b64_e32 v[20:21], v[4:5]
	v_mov_b64_e32 v[18:19], v[2:3]
	s_waitcnt lgkmcnt(0)
	s_barrier
	ds_write_b128 v190, v[98:101]
	ds_write_b128 v190, v[106:109] offset:1024
	ds_write_b128 v190, v[102:105] offset:2048
	ds_write_b128 v190, v[114:117] offset:3072
	ds_write_b128 v190, v[110:113] offset:4096
	ds_write_b128 v190, v[118:121] offset:5120
	v_add_u32_e32 v34, v185, v184
	s_mul_i32 s8, s49, 0x3000
	v_add_u32_e32 v35, v185, v189
	ds_read_b128 v[98:101], v34
	ds_read_b128 v[102:105], v34 offset:2048
	ds_read_b128 v[106:109], v35
	ds_read_b128 v[110:113], v34 offset:4096
	ds_read_b128 v[114:117], v35 offset:2048
	ds_read_b128 v[118:121], v35 offset:4096
	v_add_u32_e32 v34, s8, v182
	v_add_u32_e32 v35, v34, v184
	v_add_u32_e32 v34, v34, v189
	ds_read_b128 v[94:97], v35
	ds_read_b128 v[86:89], v35 offset:2048
	ds_read_b128 v[90:93], v34
	ds_read_b128 v[82:85], v34 offset:2048
	ds_read_b128 v[78:81], v35 offset:4096
	ds_read_b128 v[74:77], v35 offset:6144
	ds_read_b128 v[70:73], v34 offset:4096
	ds_read_b128 v[66:69], v34 offset:6144
	ds_read_b128 v[62:65], v35 offset:8192
	ds_read_b128 v[58:61], v35 offset:10240
	ds_read_b128 v[54:57], v34 offset:8192
	ds_read_b128 v[50:53], v34 offset:10240
	s_lshl_b64 s[18:19], s[0:1], 1
	s_add_u32 s26, s10, s18
	s_addc_u32 s27, s11, s19
	s_or_b32 s24, s14, 64
	s_mov_b32 s25, s15
	s_lshl_b64 s[22:23], s[24:25], 9
	s_lshl_b64 s[8:9], s[24:25], 10
	s_add_u32 s52, s26, s8
	s_addc_u32 s53, s27, s9
	s_xor_b32 s51, s49, 1
	s_mul_i32 s0, s51, 0x3000
	s_add_i32 s54, s0, s38
	s_mov_b32 s55, m0
	s_mov_b32 m0, s54
	s_nop 0
	global_load_lds_dwordx4 v1, s[52:53]
	s_mov_b32 m0, s55
	v_cndmask_b32_e64 v34, 0, 1, s[4:5]
	v_cmp_ne_u32_e64 s[8:9], 1, v34
	s_andn2_b64 vcc, exec, s[4:5]
	s_cbranch_vccnz .LBB0_1475
	s_lshl_b64 s[24:25], s[24:25], 6
	s_add_u32 s24, s16, s24
	s_addc_u32 s25, s17, s25
	s_add_i32 s0, s0, s39
	s_mov_b32 s52, m0
	s_mov_b32 m0, s0
	s_nop 0
	global_load_lds_dwordx4 v180, s[24:25]
	s_mov_b32 m0, s52

.LBB0_1478:
	s_waitcnt lgkmcnt(9)
	v_mfma_f32_32x32x16_bf16 v[66:81], v[162:165], v[106:109], v[66:81]
	s_waitcnt lgkmcnt(8)
	v_mfma_f32_32x32x16_bf16 v[82:97], v[150:153], v[106:109], v[82:97]
	s_add_u32 s26, s0, s24
	s_addc_u32 s27, s53, s25
	s_lshl_b32 s51, s57, 13
	s_add_i32 s98, s51, s43
	s_mov_b32 s99, m0
	s_mov_b32 m0, s98
	s_nop 0
	global_load_lds_dwordx4 v181, s[26:27]
	s_mov_b32 m0, s99
	s_waitcnt lgkmcnt(7)
	v_mfma_f32_32x32x16_bf16 v[66:81], v[146:149], v[102:105], v[66:81]
	s_waitcnt lgkmcnt(6)
	v_mfma_f32_32x32x16_bf16 v[82:97], v[142:145], v[102:105], v[82:97]
	s_waitcnt lgkmcnt(5)
	v_mfma_f32_32x32x16_bf16 v[66:81], v[138:141], v[114:117], v[66:81]
	ds_read_b64_tr_b16 v[150:151], v158 offset:24576
	ds_read_b64_tr_b16 v[152:153], v158 offset:25088
	ds_read_b64_tr_b16 v[146:147], v158 offset:25600
	ds_read_b64_tr_b16 v[148:149], v158 offset:26112
	ds_read_b64_tr_b16 v[142:143], v158 offset:26624
	ds_read_b64_tr_b16 v[144:145], v158 offset:27136
	ds_read_b64_tr_b16 v[138:139], v158 offset:27648
	ds_read_b64_tr_b16 v[140:141], v158 offset:28160
	s_waitcnt lgkmcnt(12)
	v_mfma_f32_32x32x16_bf16 v[82:97], v[134:137], v[114:117], v[82:97]
	s_waitcnt lgkmcnt(11)
	v_mfma_f32_32x32x16_bf16 v[66:81], v[130:133], v[110:113], v[66:81]
	s_waitcnt lgkmcnt(10)
	v_mfma_f32_32x32x16_bf16 v[82:97], v[126:129], v[110:113], v[82:97]
	s_waitcnt lgkmcnt(9)
	v_mfma_f32_32x32x16_bf16 v[66:81], v[122:125], v[118:121], v[66:81]
	ds_read_b64_tr_b16 v[134:135], v158 offset:28672
	ds_read_b64_tr_b16 v[136:137], v158 offset:29184
	ds_read_b64_tr_b16 v[130:131], v158 offset:29696
	ds_read_b64_tr_b16 v[132:133], v158 offset:30208
	ds_read_b64_tr_b16 v[126:127], v158 offset:30720
	ds_read_b64_tr_b16 v[128:129], v158 offset:31232
	ds_read_b64_tr_b16 v[122:123], v158 offset:31744
	ds_read_b64_tr_b16 v[124:125], v158 offset:32256
	s_waitcnt lgkmcnt(14)
	v_mfma_f32_32x32x16_bf16 v[82:97], v[154:157], v[118:121], v[82:97]
	s_cmp_lg_u32 s101, 0
	s_cbranch_scc0 .Lmla2_slow
	s_nop 2

.Lmla2_slow:
	s_nop 1
	v_max_f32_e32 v154, v67, v67
	v_max_f32_e32 v155, v66, v66
	v_max_f32_e32 v154, v155, v154
	s_nop 6
	v_max3_f32 v155, v68, v69, v83
	v_max3_f32 v154, v154, v82, v84
	v_max3_f32 v154, v154, v85, v70
	v_max3_f32 v155, v155, v72, v73
	v_max3_f32 v154, v154, v71, v86
	v_max3_f32 v155, v155, v88, v89
	v_max3_f32 v154, v154, v87, v74
	v_max3_f32 v155, v155, v76, v77
	v_max3_f32 v154, v154, v75, v90
	v_max3_f32 v155, v155, v92, v93
	v_max3_f32 v154, v154, v91, v78
	v_max3_f32 v155, v155, v80, v81
	v_max3_f32 v154, v154, v79, v94
	v_max3_f32 v155, v155, v96, v97
	v_max3_f32 v154, v154, v95, v155
	v_mov_b32_e32 v155, v154
	s_nop 1
	v_permlane32_swap_b32_e32 v154, v155
	v_max_f32_e32 v155, v155, v155
	v_max_f32_e32 v154, v154, v154
	v_max_f32_e32 v154, v154, v155
	v_cmp_lt_f32_e32 vcc, s47, v154
	s_cbranch_vccz .LBB0_1482
	v_max_f32_e32 v50, v154, v154
	v_max_f32_e32 v154, 0, v50
	v_exp_f32_e64 v155, -v154
	v_add_f32_e32 v171, v171, v154
	v_xor_b32_e32 v50, 0x80000000, v171
	v_mov_b32_e32 v51, v50
	v_mov_b32_e32 v52, v50
	v_mov_b32_e32 v53, v50
	v_mov_b32_e32 v54, v50
	v_mov_b32_e32 v55, v50
	v_mov_b32_e32 v56, v50
	v_mov_b32_e32 v57, v50
	v_mov_b32_e32 v58, v50
	v_mov_b32_e32 v59, v50
	v_mov_b32_e32 v60, v50
	v_mov_b32_e32 v61, v50
	v_mov_b32_e32 v62, v50
	v_mov_b32_e32 v63, v50
	v_mov_b32_e32 v64, v50
	v_mov_b32_e32 v65, v50
	s_and_saveexec_b64 s[26:27], s[6:7]
	ds_write_b32 v186, v155 offset:40960
	s_or_b64 exec, exec, s[26:27]
	v_add_u32_e32 v164, s42, v187
	ds_read_b128 v[156:159], v164 offset:41024
	ds_read_b128 v[160:163], v164 offset:41056
	ds_read_b128 v[196:199], v164 offset:40960
	ds_read_b128 v[200:203], v164 offset:40992
	v_pk_add_f32 v[66:67], v[66:67], v[154:155] op_sel_hi:[1,0] neg_lo:[0,1] neg_hi:[0,1]
	v_pk_add_f32 v[82:83], v[82:83], v[154:155] op_sel_hi:[1,0] neg_lo:[0,1] neg_hi:[0,1]
	v_pk_add_f32 v[68:69], v[68:69], v[154:155] op_sel_hi:[1,0] neg_lo:[0,1] neg_hi:[0,1]
	v_pk_add_f32 v[84:85], v[84:85], v[154:155] op_sel_hi:[1,0] neg_lo:[0,1] neg_hi:[0,1]
	v_pk_add_f32 v[70:71], v[70:71], v[154:155] op_sel_hi:[1,0] neg_lo:[0,1] neg_hi:[0,1]
	v_pk_add_f32 v[86:87], v[86:87], v[154:155] op_sel_hi:[1,0] neg_lo:[0,1] neg_hi:[0,1]
	v_pk_add_f32 v[72:73], v[72:73], v[154:155] op_sel_hi:[1,0] neg_lo:[0,1] neg_hi:[0,1]
	v_pk_add_f32 v[88:89], v[88:89], v[154:155] op_sel_hi:[1,0] neg_lo:[0,1] neg_hi:[0,1]
	v_pk_add_f32 v[74:75], v[74:75], v[154:155] op_sel_hi:[1,0] neg_lo:[0,1] neg_hi:[0,1]
	v_pk_add_f32 v[90:91], v[90:91], v[154:155] op_sel_hi:[1,0] neg_lo:[0,1] neg_hi:[0,1]
	v_pk_add_f32 v[76:77], v[76:77], v[154:155] op_sel_hi:[1,0] neg_lo:[0,1] neg_hi:[0,1]
	v_pk_add_f32 v[92:93], v[92:93], v[154:155] op_sel_hi:[1,0] neg_lo:[0,1] neg_hi:[0,1]
	v_pk_add_f32 v[78:79], v[78:79], v[154:155] op_sel_hi:[1,0] neg_lo:[0,1] neg_hi:[0,1]
	v_pk_add_f32 v[94:95], v[94:95], v[154:155] op_sel_hi:[1,0] neg_lo:[0,1] neg_hi:[0,1]
	v_pk_add_f32 v[80:81], v[80:81], v[154:155] op_sel_hi:[1,0] neg_lo:[0,1] neg_hi:[0,1]
	v_pk_add_f32 v[96:97], v[96:97], v[154:155] op_sel_hi:[1,0] neg_lo:[0,1] neg_hi:[0,1]
	v_mul_f32_e32 v173, v173, v155
	s_waitcnt lgkmcnt(2)
	v_pk_mul_f32 v[30:31], v[30:31], v[160:161]
	v_pk_mul_f32 v[26:27], v[26:27], v[156:157]
	s_waitcnt lgkmcnt(0)
	v_pk_mul_f32 v[22:23], v[22:23], v[200:201]
	v_pk_mul_f32 v[32:33], v[32:33], v[162:163]
	v_pk_mul_f32 v[28:29], v[28:29], v[158:159]
	v_pk_mul_f32 v[24:25], v[24:25], v[202:203]
	v_pk_mul_f32 v[20:21], v[20:21], v[198:199]
	v_pk_mul_f32 v[18:19], v[18:19], v[196:197]
	v_pk_mul_f32 v[46:47], v[46:47], v[160:161]
	v_pk_mul_f32 v[42:43], v[42:43], v[156:157]
	v_pk_mul_f32 v[38:39], v[38:39], v[200:201]
	v_pk_mul_f32 v[48:49], v[48:49], v[162:163]
	v_pk_mul_f32 v[44:45], v[44:45], v[158:159]
	v_pk_mul_f32 v[40:41], v[40:41], v[202:203]
	v_pk_mul_f32 v[36:37], v[36:37], v[198:199]
	v_pk_mul_f32 v[34:35], v[34:35], v[196:197]
	s_branch .LBB0_1482
